# weight-conversion slots resized to whole rounds of the converting waves (ph0 4096, idle halves 2048/4096/4096/1024, mixer phases 4096/2048)
# speedup vs baseline: 1.0120x; 1.0066x over previous
.LBB0_17:
	s_ashr_i32 s4, s4, 6
	v_writelane_b32 v254, s4, 60
	v_readlane_b32 s4, v253, 0
	v_readlane_b32 s10, v253, 6
	v_readlane_b32 s11, v253, 7
	s_add_u32 s4, s10, 0x100000
	v_writelane_b32 v254, s4, 61
	s_addc_u32 s4, s11, 0
	s_add_u32 s44, s10, 0xb100000
	s_addc_u32 s45, s11, 0
	s_add_u32 s46, s10, 0x10900000
	s_addc_u32 s47, s11, 0
	s_add_u32 s22, s10, 0x12100000
	s_addc_u32 s23, s11, 0
	s_add_u32 s52, s10, 0x12900000
	s_addc_u32 s53, s11, 0
	s_add_u32 s24, s10, 0x14900000
	v_readlane_b32 s5, v253, 1
	s_addc_u32 s25, s11, 0
	v_and_b32_e32 v189, 63, v170
	v_writelane_b32 v254, s4, 62
	s_cmp_eq_u32 s87, 1
	s_mov_b64 s[4:5], -1
	v_readlane_b32 s6, v253, 2
	v_readlane_b32 s7, v253, 3
	v_readlane_b32 s8, v253, 4
	v_readlane_b32 s9, v253, 5
	s_cbranch_scc1 .LBB0_150
	v_readlane_b32 s5, v254, 60
	s_mov_b32 s6, 0
	s_mov_b32 s8, 0
	s_mov_b32 s7, 1
	s_mov_b32 s9, 0
	s_cmp_eq_u32 s87, 2
	s_cbranch_scc0 .Lcv_attn
	s_cmp_eq_u32 s28, 0
	s_cbranch_scc0 .Lcv_s2_gemm
	s_lshl_b32 s4, s15, 3
	s_add_i32 s9, s4, s5
	s_lshl_b32 s7, s89, 3
	s_movk_i32 s6, 0x1000
	s_branch .LBB0_32
.Lcv_s2_gemm:
	s_lshl_b32 s4, s90, 1
	s_cmp_ge_i32 s4, s89
	s_cbranch_scc0 .Lcv_attn
	s_cmp_eq_u32 s28, 1
	s_cbranch_scc0 .Lcv_g6
	s_movk_i32 s8, 0x1000
	s_movk_i32 s6, 0x1800
	s_branch .Lcv_half
.Lcv_g6:
	s_cmp_eq_u32 s28, 6
	s_cbranch_scc0 .Lcv_g8
	s_movk_i32 s8, 0x2800
	s_movk_i32 s6, 0x3800
	s_branch .Lcv_half
.Lcv_g8:
	s_cmp_eq_u32 s28, 8
	s_cbranch_scc0 .Lcv_g13
	s_movk_i32 s8, 0x3800
	s_movk_i32 s6, 0x4800
	s_branch .Lcv_half
.Lcv_g13:
	s_cmp_eq_u32 s28, 13
	s_cbranch_scc0 .Lcv_attn
	s_movk_i32 s8, 0x5000
	s_movk_i32 s6, 0x5400

.Lcv_attn:
	s_cmp_eq_u32 s28, 4
	s_cbranch_scc0 .Lcv_a11
	s_movk_i32 s12, 0x1800
	s_movk_i32 s13, 0x2000
	s_movk_i32 s14, 0x2800
	s_branch .Lcv_asel
.Lcv_a11:
	s_cmp_eq_u32 s28, 11
	s_cbranch_scc0 .LBB0_32
	s_movk_i32 s12, 0x4800
	s_movk_i32 s13, 0x4c00
	s_movk_i32 s14, 0x5000
